# cache policy by consumer: ffn1 output (ACT) stored without write-through
# baseline (speedup 1.0000x reference)
;     ...
; #pragma unroll 1
;     for (int kt = 0; kt < nk - 1; ++kt) {
;       asm volatile("s_waitcnt vmcnt(0) lgkmcnt(0)" ::: "memory");
;       __builtin_amdgcn_s_barrier();
;       asm volatile("" ::: "memory");
;       G3_STEP(kt, true)
;     }
.LBB0_65:
	s_lshl_b32 s12, s3, 1
	s_and_b32 s12, s12, 0x8000
	v_lshl_or_b32 v87, v86, 1, s12
	s_waitcnt vmcnt(0) lgkmcnt(0)
	s_barrier
	v_add3_u32 v100, v87, v84, v83
	v_add3_u32 v87, v87, v82, v83
	ds_read_b128 v[88:91], v100
	ds_read_b128 v[92:95], v100 offset:2048
	ds_read_b128 v[96:99], v100 offset:4096
	ds_read_b128 v[100:103], v100 offset:6144
	ds_read_b128 v[104:107], v87 offset:16384
	ds_read_b128 v[108:111], v87 offset:18432
	ds_read_b128 v[112:115], v87 offset:20480
	ds_read_b128 v[116:119], v87 offset:22528
	v_lshl_or_b32 v87, v85, 1, s12
	v_add3_u32 v132, v87, v84, v83
	v_add3_u32 v87, v87, v82, v83
	ds_read_b128 v[120:123], v132
	ds_read_b128 v[124:127], v132 offset:2048
	ds_read_b128 v[128:131], v132 offset:4096
	ds_read_b128 v[132:135], v132 offset:6144
	ds_read_b128 v[136:139], v87 offset:16384
	ds_read_b128 v[140:143], v87 offset:18432
	ds_read_b128 v[144:147], v87 offset:20480
	ds_read_b128 v[148:151], v87 offset:22528
	s_setprio 1
	s_andn2_b32 s12, 0x8000, s11
	s_waitcnt lgkmcnt(11)
	v_mfma_f32_16x16x32_bf16 v[60:63], v[88:91], v[104:107], v[60:63]
	s_add_i32 s12, s1, s12
	v_lshl_add_u64 v[172:173], v[76:77], 0, s[6:7]
	s_add_i32 s13, s12, 0x4000
	s_mov_b32 m0, s13
	s_nop 0
	global_load_lds_dwordx4 v[172:173], off
	s_waitcnt lgkmcnt(10)
	v_mfma_f32_16x16x32_bf16 v[56:59], v[88:91], v[108:111], v[56:59]
	v_lshl_add_u64 v[152:153], v[74:75], 0, s[6:7]
	v_lshl_add_u64 v[154:155], v[64:65], 0, s[6:7]
	v_lshl_add_u64 v[156:157], v[78:79], 0, s[6:7]
	v_lshl_add_u64 v[158:159], v[68:69], 0, s[6:7]
	v_lshl_add_u64 v[166:167], v[66:67], 0, s[6:7]
	v_lshl_add_u64 v[168:169], v[72:73], 0, s[6:7]
	v_lshl_add_u64 v[170:171], v[70:71], 0, s[6:7]
	s_waitcnt lgkmcnt(9)
	v_mfma_f32_16x16x32_bf16 v[52:55], v[88:91], v[112:115], v[52:55]
	s_add_i32 s13, s12, 0x4400
	s_mov_b32 m0, s13
	s_nop 0
	global_load_lds_dwordx4 v[168:169], off
	s_waitcnt lgkmcnt(8)
	v_mfma_f32_16x16x32_bf16 v[48:51], v[88:91], v[116:119], v[48:51]
	v_mfma_f32_16x16x32_bf16 v[44:47], v[92:95], v[104:107], v[44:47]
	s_add_i32 s13, s12, 0x4800
	s_mov_b32 m0, s13
	s_nop 0
	global_load_lds_dwordx4 v[156:157], off
	v_mfma_f32_16x16x32_bf16 v[40:43], v[92:95], v[108:111], v[40:43]
	v_mfma_f32_16x16x32_bf16 v[36:39], v[92:95], v[112:115], v[36:39]
	s_add_i32 s13, s12, 0x4c00
	s_mov_b32 m0, s13
	s_nop 0
	global_load_lds_dwordx4 v[166:167], off
	v_mfma_f32_16x16x32_bf16 v[32:35], v[92:95], v[116:119], v[32:35]
	v_mfma_f32_16x16x32_bf16 v[28:31], v[96:99], v[104:107], v[28:31]
	s_add_i32 s13, s12, 0
	s_mov_b32 m0, s13
	s_nop 0
	global_load_lds_dwordx4 v[154:155], off
	v_mfma_f32_16x16x32_bf16 v[24:27], v[96:99], v[108:111], v[24:27]
	v_mfma_f32_16x16x32_bf16 v[20:23], v[96:99], v[112:115], v[20:23]
	s_add_i32 s13, s12, 0x400
	s_mov_b32 m0, s13
	s_nop 0
	global_load_lds_dwordx4 v[158:159], off
	v_mfma_f32_16x16x32_bf16 v[16:19], v[96:99], v[116:119], v[16:19]
	v_mfma_f32_16x16x32_bf16 v[12:15], v[100:103], v[104:107], v[12:15]
	s_add_i32 s13, s12, 0x800
	s_mov_b32 m0, s13
	s_nop 0
	global_load_lds_dwordx4 v[152:153], off
	v_mfma_f32_16x16x32_bf16 v[8:11], v[100:103], v[108:111], v[8:11]
	v_mfma_f32_16x16x32_bf16 v[4:7], v[100:103], v[112:115], v[4:7]
	s_addk_i32 s12, 0xc00
	s_mov_b32 m0, s12
	s_nop 0
	global_load_lds_dwordx4 v[170:171], off
	v_mfma_f32_16x16x32_bf16 v[0:3], v[100:103], v[116:119], v[0:3]
	s_waitcnt lgkmcnt(3)
	v_mfma_f32_16x16x32_bf16 v[60:63], v[120:123], v[136:139], v[60:63]
	s_waitcnt lgkmcnt(2)
	v_mfma_f32_16x16x32_bf16 v[56:59], v[120:123], v[140:143], v[56:59]
	s_waitcnt lgkmcnt(1)
	v_mfma_f32_16x16x32_bf16 v[52:55], v[120:123], v[144:147], v[52:55]
	s_waitcnt lgkmcnt(0)
	v_mfma_f32_16x16x32_bf16 v[48:51], v[120:123], v[148:151], v[48:51]
	v_mfma_f32_16x16x32_bf16 v[44:47], v[124:127], v[136:139], v[44:47]
	v_mfma_f32_16x16x32_bf16 v[40:43], v[124:127], v[140:143], v[40:43]
	v_mfma_f32_16x16x32_bf16 v[36:39], v[124:127], v[144:147], v[36:39]
	v_mfma_f32_16x16x32_bf16 v[32:35], v[124:127], v[148:151], v[32:35]
	v_mfma_f32_16x16x32_bf16 v[28:31], v[128:131], v[136:139], v[28:31]
	v_mfma_f32_16x16x32_bf16 v[24:27], v[128:131], v[140:143], v[24:27]
	v_mfma_f32_16x16x32_bf16 v[20:23], v[128:131], v[144:147], v[20:23]
	v_mfma_f32_16x16x32_bf16 v[16:19], v[128:131], v[148:151], v[16:19]
	v_mfma_f32_16x16x32_bf16 v[12:15], v[132:135], v[136:139], v[12:15]
	v_mfma_f32_16x16x32_bf16 v[8:11], v[132:135], v[140:143], v[8:11]
	v_mfma_f32_16x16x32_bf16 v[4:7], v[132:135], v[144:147], v[4:7]
	v_mfma_f32_16x16x32_bf16 v[0:3], v[132:135], v[148:151], v[0:3]
	s_setprio 0
	s_add_i32 s11, s11, 0x8000
	s_add_u32 s6, s6, 0x80
	s_addc_u32 s7, s7, 0
	s_addk_i32 s3, 0x4000
	s_cmpk_lg_i32 s6, 0x780
	s_cbranch_scc1 .LBB0_65
	v_lshlrev_b32_e32 v86, 1, v86
	v_lshlrev_b32_e32 v85, 1, v85
	s_waitcnt vmcnt(0) lgkmcnt(0)
	s_barrier
; DI float siluf_(float x) { return x * sigmoidf_(x); }
;     ...
;     asm volatile("s_waitcnt vmcnt(0) lgkmcnt(0)" ::: "memory");
;     __builtin_amdgcn_s_barrier();
;     asm volatile("" ::: "memory");
;     G3_STEP(nk - 1, false)
; DI void ffn1_tile(const Params& P, int l, int it, u16* sA, u16* sB) {
;     ...
;   __syncthreads();
; #pragma unroll
;   for (int mi = 0; mi < 4; ++mi)
; #pragma unroll
;     for (int ni = 0; ni < 2; ++ni)
; #pragma unroll
;       for (int j = 0; j < 4; ++j)
;         sA[(wm * 64 + 16 * mi + 4 * quad + j) * 72 + wn * 32 + 16 * ni + r16] = f2bf(siluf_(acc[mi][ni][j]) * acc[mi][ni + 2][j]);
	v_add3_u32 v76, v86, v84, v83
	v_add3_u32 v98, v86, v82, v83
	v_add3_u32 v84, v85, v84, v83
	v_add3_u32 v126, v85, v82, v83
	ds_read_b128 v[64:67], v76 offset:32768
	ds_read_b128 v[68:71], v76 offset:34816
	ds_read_b128 v[72:75], v76 offset:36864
	ds_read_b128 v[76:79], v76 offset:38912
	ds_read_b128 v[86:89], v98 offset:49152
	ds_read_b128 v[90:93], v98 offset:51200
	ds_read_b128 v[94:97], v98 offset:53248
	ds_read_b128 v[98:101], v98 offset:55296
	ds_read_b128 v[102:105], v84 offset:32768
	ds_read_b128 v[106:109], v84 offset:34816
	ds_read_b128 v[110:113], v84 offset:36864
	ds_read_b128 v[114:117], v84 offset:38912
	ds_read_b128 v[82:85], v126 offset:49152
	ds_read_b128 v[118:121], v126 offset:51200
	ds_read_b128 v[122:125], v126 offset:53248
	ds_read_b128 v[126:129], v126 offset:55296
	v_and_b32_e32 v138, 15, v80
	s_setprio 1
	s_waitcnt lgkmcnt(11)
	v_mfma_f32_16x16x32_bf16 v[60:63], v[64:67], v[86:89], v[60:63]
	s_waitcnt lgkmcnt(10)
	v_mfma_f32_16x16x32_bf16 v[56:59], v[64:67], v[90:93], v[56:59]
	s_waitcnt lgkmcnt(9)
	v_mfma_f32_16x16x32_bf16 v[52:55], v[64:67], v[94:97], v[52:55]
	s_waitcnt lgkmcnt(8)
	v_mfma_f32_16x16x32_bf16 v[64:67], v[64:67], v[98:101], v[48:51]
	v_mfma_f32_16x16x32_bf16 v[44:47], v[68:71], v[86:89], v[44:47]
	v_mfma_f32_16x16x32_bf16 v[130:133], v[68:71], v[90:93], v[40:43]
	v_mfma_f32_16x16x32_bf16 v[36:39], v[68:71], v[94:97], v[36:39]
	v_mfma_f32_16x16x32_bf16 v[68:71], v[68:71], v[98:101], v[32:35]
	v_mfma_f32_16x16x32_bf16 v[28:31], v[72:75], v[86:89], v[28:31]
	v_mfma_f32_16x16x32_bf16 v[134:137], v[72:75], v[90:93], v[24:27]
	v_mfma_f32_16x16x32_bf16 v[20:23], v[72:75], v[94:97], v[20:23]
	v_mfma_f32_16x16x32_bf16 v[72:75], v[72:75], v[98:101], v[16:19]
	v_mfma_f32_16x16x32_bf16 v[12:15], v[76:79], v[86:89], v[12:15]
	v_mfma_f32_16x16x32_bf16 v[86:89], v[76:79], v[90:93], v[8:11]
	v_mfma_f32_16x16x32_bf16 v[4:7], v[76:79], v[94:97], v[4:7]
	v_mfma_f32_16x16x32_bf16 v[76:79], v[76:79], v[98:101], v[0:3]
	s_waitcnt lgkmcnt(2)
	v_mfma_f32_16x16x32_bf16 v[0:3], v[114:117], v[118:121], v[86:89]
	v_mfma_f32_16x16x32_bf16 v[60:63], v[102:105], v[82:85], v[60:63]
	v_mfma_f32_16x16x32_bf16 v[48:51], v[102:105], v[118:121], v[56:59]
	s_waitcnt lgkmcnt(1)
	v_mfma_f32_16x16x32_bf16 v[90:93], v[102:105], v[122:125], v[52:55]
	s_waitcnt lgkmcnt(0)
	v_mfma_f32_16x16x32_bf16 v[52:55], v[102:105], v[126:129], v[64:67]
	v_mfma_f32_16x16x32_bf16 v[40:43], v[106:109], v[82:85], v[44:47]
	v_mfma_f32_16x16x32_bf16 v[32:35], v[106:109], v[118:121], v[130:133]
	v_mfma_f32_16x16x32_bf16 v[44:47], v[106:109], v[122:125], v[36:39]
	v_mfma_f32_16x16x32_bf16 v[36:39], v[106:109], v[126:129], v[68:71]
	v_mfma_f32_16x16x32_bf16 v[24:27], v[110:113], v[82:85], v[28:31]
	v_mfma_f32_16x16x32_bf16 v[16:19], v[110:113], v[118:121], v[134:137]
	v_mfma_f32_16x16x32_bf16 v[28:31], v[110:113], v[122:125], v[20:23]
	v_mfma_f32_16x16x32_bf16 v[20:23], v[110:113], v[126:129], v[72:75]
	v_mfma_f32_16x16x32_bf16 v[8:11], v[114:117], v[82:85], v[12:15]
	v_mfma_f32_16x16x32_bf16 v[12:15], v[114:117], v[122:125], v[4:7]
	v_mfma_f32_16x16x32_bf16 v[4:7], v[114:117], v[126:129], v[76:79]
	s_setprio 0
	v_lshrrev_b32_e32 v56, 2, v80
	v_and_b32_e32 v56, 12, v56
	s_mov_b32 s1, 0xfffffc0
	v_and_or_b32 v57, v81, s1, v56
	v_lshlrev_b32_e32 v56, 1, v138
	v_and_or_b32 v56, v80, 64, v56
	v_mad_u64_u32 v[56:57], s[6:7], v57, s54, v[56:57]
	v_mul_f32_e32 v57, 0xbfb8aa3b, v61
	v_exp_f32_e32 v57, v57
	s_barrier
	v_add_f32_e32 v57, 1.0, v57
	v_rcp_f32_e32 v57, v57
	v_mul_f32_e32 v58, 0xbfb8aa3b, v60
	v_exp_f32_e32 v58, v58
	s_add_u32 s1, s70, s4
	v_mul_f32_e32 v57, v61, v57
	v_mul_f32_e32 v57, v91, v57
	v_cvt_pk_bf16_f32 v57, v57, s0
	ds_write_b16 v56, v57 offset:144
	v_mul_f32_e32 v57, 0xbfb8aa3b, v62
	v_exp_f32_e32 v57, v57
	v_add_f32_e32 v58, 1.0, v58
	v_rcp_f32_e32 v58, v58
	s_addc_u32 s3, s71, s5
	v_add_f32_e32 v57, 1.0, v57
	v_rcp_f32_e32 v57, v57
	v_mul_f32_e32 v58, v60, v58
	s_mul_hi_i32 s4, s2, 0xb0000
	s_mul_i32 s2, s2, 0xb0000
	v_mul_f32_e32 v57, v62, v57
	v_mul_f32_e32 v57, v92, v57
	v_cvt_pk_bf16_f32 v57, v57, s0
	ds_write_b16 v56, v57 offset:288
	v_mul_f32_e32 v57, 0xbfb8aa3b, v63
	v_exp_f32_e32 v57, v57
	v_mul_f32_e32 v58, v90, v58
	s_add_u32 s2, s1, s2
	v_cvt_pk_bf16_f32 v58, v58, s0
	v_add_f32_e32 v57, 1.0, v57
	v_rcp_f32_e32 v57, v57
	s_addc_u32 s3, s3, s4
	ds_write_b16 v56, v58
	v_mul_f32_e32 v57, v63, v57
	v_mul_f32_e32 v57, v93, v57
	v_cvt_pk_bf16_f32 v57, v57, s0
	ds_write_b16 v56, v57 offset:432
	v_mul_f32_e32 v57, 0xbfb8aa3b, v48
	v_exp_f32_e32 v57, v57
	s_nop 0
	v_add_f32_e32 v57, 1.0, v57
	v_rcp_f32_e32 v57, v57
	s_nop 0
	v_mul_f32_e32 v48, v48, v57
	v_mul_f32_e32 v48, v52, v48
	v_cvt_pk_bf16_f32 v48, v48, s0
	ds_write_b16 v56, v48 offset:32
	v_mul_f32_e32 v48, 0xbfb8aa3b, v49
	v_exp_f32_e32 v48, v48
	s_nop 0
	v_add_f32_e32 v48, 1.0, v48
	v_rcp_f32_e32 v48, v48
	s_nop 0
	v_mul_f32_e32 v48, v49, v48
	v_mul_f32_e32 v48, v53, v48
	v_cvt_pk_bf16_f32 v48, v48, s0
	ds_write_b16 v56, v48 offset:176
	v_mul_f32_e32 v48, 0xbfb8aa3b, v50
	v_exp_f32_e32 v48, v48
	s_nop 0
	v_add_f32_e32 v48, 1.0, v48
	v_rcp_f32_e32 v48, v48
	s_nop 0
	v_mul_f32_e32 v48, v50, v48
	v_mul_f32_e32 v48, v54, v48
	v_cvt_pk_bf16_f32 v48, v48, s0
	ds_write_b16 v56, v48 offset:320
	v_mul_f32_e32 v48, 0xbfb8aa3b, v51
	v_exp_f32_e32 v48, v48
	s_nop 0
	v_add_f32_e32 v48, 1.0, v48
	v_rcp_f32_e32 v48, v48
	s_nop 0
	v_mul_f32_e32 v48, v51, v48
	v_mul_f32_e32 v48, v55, v48
	v_cvt_pk_bf16_f32 v48, v48, s0
	ds_write_b16 v56, v48 offset:464
	v_mul_f32_e32 v48, 0xbfb8aa3b, v40
	v_exp_f32_e32 v48, v48
	s_nop 0
	v_add_f32_e32 v48, 1.0, v48
	v_rcp_f32_e32 v48, v48
	s_nop 0
	v_mul_f32_e32 v40, v40, v48
; DI int TID() { int t = threadIdx.x; asm volatile("" : "+v"(t)); return t; }
; DI float siluf_(float x) { return x * sigmoidf_(x); }
; template <int NCOLS>
; DI void store_tile_bf16(const u16* sC, u16* gdst, long ld, int rows_valid) {
;   constexpr int CPR = NCOLS / 8, LS = NCOLS + 8;
;   const int tid = TID();
; #pragma unroll
;   for (int q = 0; q < (128 * CPR) / 256; ++q) {
;     const int c = tid + 256 * q, row = c / CPR, ch = c % CPR;
;     if (row < rows_valid) *(uint4*)(gdst + (long)row * ld + ch * 8) = *(const uint4*)(sC + row * LS + ch * 8);
;   }
; DI void ffn1_tile(const Params& P, int l, int it, u16* sA, u16* sB) {
;     ...
;   __syncthreads();
; #pragma unroll
;   for (int mi = 0; mi < 4; ++mi)
; #pragma unroll
;     for (int ni = 0; ni < 2; ++ni)
; #pragma unroll
;       for (int j = 0; j < 4; ++j)
;         sA[(wm * 64 + 16 * mi + 4 * quad + j) * 72 + wn * 32 + 16 * ni + r16] = f2bf(siluf_(acc[mi][ni][j]) * acc[mi][ni + 2][j]);
;   __syncthreads();
;   store_tile_bf16<64>(sA, ACT + (long)mt * 128 * DFF + nt * 64, DFF, 128);
	v_mul_f32_e32 v40, v44, v40
	v_cvt_pk_bf16_f32 v40, v40, s0
	ds_write_b16 v56, v40 offset:2304
	v_mul_f32_e32 v40, 0xbfb8aa3b, v41
	v_exp_f32_e32 v40, v40
	s_nop 0
	v_add_f32_e32 v40, 1.0, v40
	v_rcp_f32_e32 v40, v40
	s_nop 0
	v_mul_f32_e32 v40, v41, v40
	v_mul_f32_e32 v40, v45, v40
	v_cvt_pk_bf16_f32 v40, v40, s0
	ds_write_b16 v56, v40 offset:2448
	v_mul_f32_e32 v40, 0xbfb8aa3b, v42
	v_exp_f32_e32 v40, v40
	s_nop 0
	v_add_f32_e32 v40, 1.0, v40
	v_rcp_f32_e32 v40, v40
	s_nop 0
	v_mul_f32_e32 v40, v42, v40
	v_mul_f32_e32 v40, v46, v40
	v_cvt_pk_bf16_f32 v40, v40, s0
	ds_write_b16 v56, v40 offset:2592
	v_mul_f32_e32 v40, 0xbfb8aa3b, v43
	v_exp_f32_e32 v40, v40
	s_nop 0
	v_add_f32_e32 v40, 1.0, v40
	v_rcp_f32_e32 v40, v40
	s_nop 0
	v_mul_f32_e32 v40, v43, v40
	v_mul_f32_e32 v40, v47, v40
	v_cvt_pk_bf16_f32 v40, v40, s0
	ds_write_b16 v56, v40 offset:2736
	v_mul_f32_e32 v40, 0xbfb8aa3b, v32
	v_exp_f32_e32 v40, v40
	s_nop 0
	v_add_f32_e32 v40, 1.0, v40
	v_rcp_f32_e32 v40, v40
	s_nop 0
	v_mul_f32_e32 v32, v32, v40
	v_mul_f32_e32 v32, v36, v32
	v_cvt_pk_bf16_f32 v32, v32, s0
	ds_write_b16 v56, v32 offset:2336
	v_mul_f32_e32 v32, 0xbfb8aa3b, v33
	v_exp_f32_e32 v32, v32
	s_nop 0
	v_add_f32_e32 v32, 1.0, v32
	v_rcp_f32_e32 v32, v32
	s_nop 0
	v_mul_f32_e32 v32, v33, v32
	v_mul_f32_e32 v32, v37, v32
	v_cvt_pk_bf16_f32 v32, v32, s0
	ds_write_b16 v56, v32 offset:2480
	v_mul_f32_e32 v32, 0xbfb8aa3b, v34
	v_exp_f32_e32 v32, v32
	s_nop 0
	v_add_f32_e32 v32, 1.0, v32
	v_rcp_f32_e32 v32, v32
	s_nop 0
	v_mul_f32_e32 v32, v34, v32
	v_mul_f32_e32 v32, v38, v32
	v_cvt_pk_bf16_f32 v32, v32, s0
	ds_write_b16 v56, v32 offset:2624
	v_mul_f32_e32 v32, 0xbfb8aa3b, v35
	v_exp_f32_e32 v32, v32
	s_nop 0
	v_add_f32_e32 v32, 1.0, v32
	v_rcp_f32_e32 v32, v32
	s_nop 0
	v_mul_f32_e32 v32, v35, v32
	v_mul_f32_e32 v32, v39, v32
	v_cvt_pk_bf16_f32 v32, v32, s0
	ds_write_b16 v56, v32 offset:2768
	v_mul_f32_e32 v32, 0xbfb8aa3b, v24
	v_exp_f32_e32 v32, v32
	s_nop 0
	v_add_f32_e32 v32, 1.0, v32
	v_rcp_f32_e32 v32, v32
	s_nop 0
	v_mul_f32_e32 v24, v24, v32
	v_mul_f32_e32 v24, v28, v24
	v_cvt_pk_bf16_f32 v24, v24, s0
	ds_write_b16 v56, v24 offset:4608
	v_mul_f32_e32 v24, 0xbfb8aa3b, v25
	v_exp_f32_e32 v24, v24
	s_nop 0
	v_add_f32_e32 v24, 1.0, v24
	v_rcp_f32_e32 v24, v24
	s_nop 0
	v_mul_f32_e32 v24, v25, v24
	v_mul_f32_e32 v24, v29, v24
	v_cvt_pk_bf16_f32 v24, v24, s0
	ds_write_b16 v56, v24 offset:4752
	v_mul_f32_e32 v24, 0xbfb8aa3b, v26
	v_exp_f32_e32 v24, v24
	s_nop 0
	v_add_f32_e32 v24, 1.0, v24
	v_rcp_f32_e32 v24, v24
	s_nop 0
	v_mul_f32_e32 v24, v26, v24
	v_mul_f32_e32 v24, v30, v24
	v_cvt_pk_bf16_f32 v24, v24, s0
	ds_write_b16 v56, v24 offset:4896
	v_mul_f32_e32 v24, 0xbfb8aa3b, v27
	v_exp_f32_e32 v24, v24
	s_nop 0
	v_add_f32_e32 v24, 1.0, v24
	v_rcp_f32_e32 v24, v24
	s_nop 0
	v_mul_f32_e32 v24, v27, v24
	v_mul_f32_e32 v24, v31, v24
	v_cvt_pk_bf16_f32 v24, v24, s0
	ds_write_b16 v56, v24 offset:5040
	v_mul_f32_e32 v24, 0xbfb8aa3b, v16
	v_exp_f32_e32 v24, v24
	s_nop 0
	v_add_f32_e32 v24, 1.0, v24
	v_rcp_f32_e32 v24, v24
	s_nop 0
	v_mul_f32_e32 v16, v16, v24
	v_mul_f32_e32 v16, v20, v16
	v_cvt_pk_bf16_f32 v16, v16, s0
	ds_write_b16 v56, v16 offset:4640
	v_mul_f32_e32 v16, 0xbfb8aa3b, v17
	v_exp_f32_e32 v16, v16
	s_nop 0
	v_add_f32_e32 v16, 1.0, v16
	v_rcp_f32_e32 v16, v16
	s_nop 0
	v_mul_f32_e32 v16, v17, v16
	v_mul_f32_e32 v16, v21, v16
	v_cvt_pk_bf16_f32 v16, v16, s0
	ds_write_b16 v56, v16 offset:4784
	v_mul_f32_e32 v16, 0xbfb8aa3b, v18
	v_exp_f32_e32 v16, v16
	s_nop 0
	v_add_f32_e32 v16, 1.0, v16
	v_rcp_f32_e32 v16, v16
	s_nop 0
	v_mul_f32_e32 v16, v18, v16
	v_mul_f32_e32 v16, v22, v16
	v_cvt_pk_bf16_f32 v16, v16, s0
	ds_write_b16 v56, v16 offset:4928
	v_mul_f32_e32 v16, 0xbfb8aa3b, v19
	v_exp_f32_e32 v16, v16
	s_nop 0
	v_add_f32_e32 v16, 1.0, v16
	v_rcp_f32_e32 v16, v16
	s_nop 0
	v_mul_f32_e32 v16, v19, v16
	v_mul_f32_e32 v16, v23, v16
	v_cvt_pk_bf16_f32 v16, v16, s0
	ds_write_b16 v56, v16 offset:5072
	v_mul_f32_e32 v16, 0xbfb8aa3b, v8
	v_exp_f32_e32 v16, v16
	s_nop 0
	v_add_f32_e32 v16, 1.0, v16
	v_rcp_f32_e32 v16, v16
	s_nop 0
	v_mul_f32_e32 v8, v8, v16
	v_mul_f32_e32 v8, v12, v8
	v_cvt_pk_bf16_f32 v8, v8, s0
	ds_write_b16 v56, v8 offset:6912
	v_mul_f32_e32 v8, 0xbfb8aa3b, v9
	v_exp_f32_e32 v8, v8
	s_nop 0
	v_add_f32_e32 v8, 1.0, v8
	v_rcp_f32_e32 v8, v8
	s_nop 0
	v_mul_f32_e32 v8, v9, v8
	v_mul_f32_e32 v8, v13, v8
	v_cvt_pk_bf16_f32 v8, v8, s0
	ds_write_b16 v56, v8 offset:7056
	v_mul_f32_e32 v8, 0xbfb8aa3b, v10
	v_exp_f32_e32 v8, v8
	s_nop 0
	v_add_f32_e32 v8, 1.0, v8
	v_rcp_f32_e32 v8, v8
	s_nop 0
	v_mul_f32_e32 v8, v10, v8
	v_mul_f32_e32 v8, v14, v8
	v_cvt_pk_bf16_f32 v8, v8, s0
	ds_write_b16 v56, v8 offset:7200
	v_mul_f32_e32 v8, 0xbfb8aa3b, v11
	v_exp_f32_e32 v8, v8
	s_nop 0
	v_add_f32_e32 v8, 1.0, v8
	v_rcp_f32_e32 v8, v8
	s_nop 0
	v_mul_f32_e32 v8, v11, v8
	v_mul_f32_e32 v8, v15, v8
	v_cvt_pk_bf16_f32 v8, v8, s0
	ds_write_b16 v56, v8 offset:7344
	v_mul_f32_e32 v8, 0xbfb8aa3b, v0
	v_exp_f32_e32 v8, v8
	s_nop 0
	v_add_f32_e32 v8, 1.0, v8
	v_rcp_f32_e32 v8, v8
	s_nop 0
	v_mul_f32_e32 v0, v0, v8
	v_mul_f32_e32 v0, v4, v0
	v_cvt_pk_bf16_f32 v0, v0, s0
	ds_write_b16 v56, v0 offset:6944
	v_mul_f32_e32 v0, 0xbfb8aa3b, v1
	v_exp_f32_e32 v0, v0
	s_nop 0
	v_add_f32_e32 v0, 1.0, v0
	v_rcp_f32_e32 v0, v0
	s_nop 0
	v_mul_f32_e32 v0, v1, v0
	v_mul_f32_e32 v0, v5, v0
	v_cvt_pk_bf16_f32 v0, v0, s0
	ds_write_b16 v56, v0 offset:7088
	v_mul_f32_e32 v0, 0xbfb8aa3b, v2
	v_exp_f32_e32 v0, v0
	s_nop 0
	v_add_f32_e32 v0, 1.0, v0
	v_rcp_f32_e32 v0, v0
	s_nop 0
	v_mul_f32_e32 v0, v2, v0
	v_mul_f32_e32 v0, v6, v0
	v_cvt_pk_bf16_f32 v0, v0, s0
	ds_write_b16 v56, v0 offset:7232
	v_mul_f32_e32 v0, 0xbfb8aa3b, v3
	v_exp_f32_e32 v0, v0
	s_nop 0
	v_add_f32_e32 v0, 1.0, v0
	v_rcp_f32_e32 v0, v0
	s_nop 0
	v_mul_f32_e32 v0, v3, v0
	v_mul_f32_e32 v0, v7, v0
	v_cvt_pk_bf16_f32 v0, v0, s0
	s_lshl_b32 s0, s0, 6
	s_ashr_i32 s1, s0, 31
	s_lshl_b64 s[0:1], s[0:1], 1
	s_add_u32 s0, s2, s0
	s_addc_u32 s1, s3, s1
	ds_write_b16 v56, v0 offset:7376
	s_add_u32 s0, s0, 0x4000000
	v_mov_b32_e32 v0, v160
	s_movk_i32 s2, 0x400
	s_waitcnt lgkmcnt(0)
	s_barrier
	s_addc_u32 s1, s1, 0
	s_nop 0
	v_cmp_gt_i32_e32 vcc, s2, v0
	s_and_saveexec_b64 s[2:3], vcc
	s_cbranch_execz .LBB0_68
	v_ashrrev_i32_e32 v1, 31, v0
	v_lshrrev_b32_e32 v1, 29, v1
	v_add_u32_e32 v1, v0, v1
	v_ashrrev_i32_e32 v6, 3, v1
	v_and_b32_e32 v1, -8, v1
	v_sub_u32_e32 v1, v0, v1
	v_mul_lo_u32 v4, v6, s54
	v_lshlrev_b32_e32 v2, 3, v1
	v_lshl_add_u32 v1, v1, 4, v4
	v_mov_b64_e32 v[4:5], s[0:1]
	s_movk_i32 s4, 0x1600
	v_ashrrev_i32_e32 v3, 31, v2
	v_mad_i64_i32 v[4:5], s[4:5], v6, s4, v[4:5]
	v_lshl_add_u64 v[6:7], v[2:3], 1, v[4:5]
	ds_read_b128 v[2:5], v1
	s_waitcnt lgkmcnt(0)
	global_store_dwordx4 v[6:7], v[2:5], off
